# prep phase adaLN GEMV k loop: scalar v_fmac_f32 instead of packed-f32 FMAs and their register shuffles
# baseline (speedup 1.0000x reference)
.Lmod_body:
	ds_read_b128 v[10:13], v74
	ds_read_b128 v[6:9], v74 offset:16
	ds_read_b128 v[2:5], v74 offset:4096
	ds_read_b128 v[14:17], v74 offset:4112
	ds_read_b128 v[42:45], v74 offset:8192
	ds_read_b128 v[34:37], v74 offset:8208
	ds_read_b128 v[26:29], v74 offset:12288
	ds_read_b128 v[18:21], v74 offset:12304
	ds_read_b128 v[58:61], v74 offset:16384
	ds_read_b128 v[50:53], v74 offset:16400
	ds_read_b128 v[30:33], v74 offset:20480
	ds_read_b128 v[22:25], v74 offset:20496
	ds_read_b128 v[70:73], v74 offset:24576
	ds_read_b128 v[62:65], v74 offset:24592
	ds_read_b128 v[38:41], v74 offset:28672
	ds_read_b128 v[46:49], v74 offset:28688
	ds_read_b128 v[66:69], v74 offset:32768
	ds_read_b128 v[54:57], v74 offset:32784
	s_add_u32 s18, s18, 0x18000
	s_addc_u32 s19, s19, 0
	v_add_u32_e32 v74, 32, v74
	s_waitcnt lgkmcnt(15)
	v_fmac_f32_e32 v102, v132, v10
	v_fmac_f32_e32 v102, v134, v11
	v_fmac_f32_e32 v102, v136, v12
	v_fmac_f32_e32 v102, v138, v13
	v_fmac_f32_e32 v102, v140, v6
	v_fmac_f32_e32 v102, v142, v7
	v_fmac_f32_e32 v102, v144, v8
	v_fmac_f32_e32 v102, v110, v9
	s_waitcnt lgkmcnt(14)
	v_fmac_f32_e32 v103, v132, v2
	v_fmac_f32_e32 v103, v134, v3
	v_fmac_f32_e32 v103, v136, v4
	v_fmac_f32_e32 v103, v138, v5
	v_fmac_f32_e32 v103, v140, v14
	v_fmac_f32_e32 v103, v142, v15
	v_fmac_f32_e32 v103, v144, v16
	v_fmac_f32_e32 v103, v110, v17
	s_waitcnt lgkmcnt(12)
	v_fmac_f32_e32 v104, v132, v42
	v_fmac_f32_e32 v104, v134, v43
	v_fmac_f32_e32 v104, v136, v44
	v_fmac_f32_e32 v104, v138, v45
	v_fmac_f32_e32 v104, v140, v34
	v_fmac_f32_e32 v104, v142, v35
	v_fmac_f32_e32 v104, v144, v36
	v_fmac_f32_e32 v104, v110, v37
	s_waitcnt lgkmcnt(10)
	v_fmac_f32_e32 v105, v132, v26
	v_fmac_f32_e32 v105, v134, v27
	v_fmac_f32_e32 v105, v136, v28
	v_fmac_f32_e32 v105, v138, v29
	v_fmac_f32_e32 v105, v140, v18
	v_fmac_f32_e32 v105, v142, v19
	v_fmac_f32_e32 v105, v144, v20
	v_fmac_f32_e32 v105, v110, v21
	s_waitcnt lgkmcnt(8)
	v_fmac_f32_e32 v106, v132, v58
	v_fmac_f32_e32 v106, v134, v59
	v_fmac_f32_e32 v106, v136, v60
	v_fmac_f32_e32 v106, v138, v61
	v_fmac_f32_e32 v106, v140, v50
	v_fmac_f32_e32 v106, v142, v51
	v_fmac_f32_e32 v106, v144, v52
	v_fmac_f32_e32 v106, v110, v53
	s_waitcnt lgkmcnt(6)
	v_fmac_f32_e32 v107, v132, v30
	v_fmac_f32_e32 v107, v134, v31
	v_fmac_f32_e32 v107, v136, v32
	v_fmac_f32_e32 v107, v138, v33
	v_fmac_f32_e32 v107, v140, v22
	v_fmac_f32_e32 v107, v142, v23
	v_fmac_f32_e32 v107, v144, v24
	v_fmac_f32_e32 v107, v110, v25
	s_waitcnt lgkmcnt(4)
	v_fmac_f32_e32 v108, v132, v70
	v_fmac_f32_e32 v108, v134, v71
	v_fmac_f32_e32 v108, v136, v72
	v_fmac_f32_e32 v108, v138, v73
	v_fmac_f32_e32 v108, v140, v62
	v_fmac_f32_e32 v108, v142, v63
	v_fmac_f32_e32 v108, v144, v64
	v_fmac_f32_e32 v108, v110, v65
	s_waitcnt lgkmcnt(2)
	v_fmac_f32_e32 v109, v132, v38
	v_fmac_f32_e32 v109, v134, v39
	v_fmac_f32_e32 v109, v136, v40
	v_fmac_f32_e32 v109, v138, v41
	v_fmac_f32_e32 v109, v140, v46
	v_fmac_f32_e32 v109, v142, v47
	v_fmac_f32_e32 v109, v144, v48
	v_fmac_f32_e32 v109, v110, v49
	s_waitcnt lgkmcnt(0)
	v_fmac_f32_e32 v99, v132, v66
	v_fmac_f32_e32 v99, v134, v67
	v_fmac_f32_e32 v99, v136, v68
	v_fmac_f32_e32 v99, v138, v69
	v_fmac_f32_e32 v99, v140, v54
	v_fmac_f32_e32 v99, v142, v55
	v_fmac_f32_e32 v99, v144, v56
	v_fmac_f32_e32 v99, v110, v57
	s_cmp_eq_u32 s18, 0xc0000
	s_cbranch_scc0 .LBB0_88
	v_add_u32_e32 v2, 0x9000, v121
	ds_write2_b32 v2, v102, v103 offset1:32
	ds_write2_b32 v2, v104, v105 offset0:64 offset1:96
	ds_write2_b32 v2, v106, v107 offset0:128 offset1:160
	ds_write2_b32 v2, v108, v109 offset0:192 offset1:224
	ds_write_b32 v121, v99 offset:37888
	s_waitcnt lgkmcnt(0)
	s_barrier
	s_and_saveexec_b64 s[18:19], s[8:9]
	s_cbranch_execz .LBB0_55
	s_lshl_b32 s20, s74, 5
	v_or_b32_e32 v2, s20, v113
	v_ashrrev_i32_e32 v3, 31, v2
	v_lshl_add_u64 v[2:3], v[2:3], 2, s[30:31]
	global_load_dword v4, v[2:3], off
	ds_read_b32 v5, v122 offset:36864
	ds_read_b32 v6, v122 offset:38016
	ds_read_b32 v7, v122 offset:39168
	ds_read_b32 v8, v122 offset:40320
	ds_read_b32 v9, v122 offset:41472
	ds_read_b32 v10, v122 offset:42624
	ds_read_b32 v11, v122 offset:43776
	ds_read_b32 v12, v122 offset:44928
	ds_read_b32 v13, v122 offset:46080
	ds_read_b32 v14, v122 offset:47232
	ds_read_b32 v15, v122 offset:48384
	ds_read_b32 v16, v122 offset:49536
	ds_read_b32 v17, v122 offset:50688
	ds_read_b32 v18, v122 offset:51840
	ds_read_b32 v19, v122 offset:52992
	ds_read_b32 v20, v122 offset:54144
	s_waitcnt lgkmcnt(14)
	v_add_f32_e32 v5, 0, v5
	v_add_f32_e32 v5, v5, v6
	s_waitcnt lgkmcnt(13)
	v_add_f32_e32 v5, v5, v7
	s_waitcnt lgkmcnt(12)
	v_add_f32_e32 v5, v5, v8
	s_waitcnt lgkmcnt(11)
	v_add_f32_e32 v5, v5, v9
	s_waitcnt lgkmcnt(10)
	v_add_f32_e32 v5, v5, v10
	s_waitcnt lgkmcnt(9)
	v_add_f32_e32 v5, v5, v11
	s_waitcnt lgkmcnt(8)
	v_add_f32_e32 v5, v5, v12
	s_waitcnt lgkmcnt(7)
	v_add_f32_e32 v5, v5, v13
	s_waitcnt lgkmcnt(6)
	v_add_f32_e32 v5, v5, v14
	s_waitcnt lgkmcnt(5)
	v_add_f32_e32 v5, v5, v15
	s_waitcnt lgkmcnt(4)
	v_add_f32_e32 v5, v5, v16
	s_waitcnt lgkmcnt(3)
	v_add_f32_e32 v5, v5, v17
	s_waitcnt lgkmcnt(2)
	v_add_f32_e32 v5, v5, v18
	v_add_u32_e32 v2, s20, v116
	s_waitcnt lgkmcnt(1)
	v_add_f32_e32 v5, v5, v19
	v_ashrrev_i32_e32 v3, 31, v2
	s_waitcnt lgkmcnt(0)
	v_add_f32_e32 v5, v5, v20
	v_lshl_add_u64 v[2:3], v[2:3], 2, s[40:41]
	s_waitcnt vmcnt(0)
	v_add_f32_e32 v4, v5, v4
	global_store_dword v[2:3], v4, off
	s_branch .LBB0_55
